# speedup vs baseline: 1.0025x; 1.0025x over previous
; __device__ __forceinline__ void gemm_tile(const TileDesc& td, char* shm_c, const int wv) {
;     ...
;   } else if (mode == EPI_ROPE_A) {
;     const float sc = td.scale;
;     #pragma unroll
;     for (int bj = 0; bj < 2; ++bj)
;     #pragma unroll
;     for (int n = 0; n < 2; ++n) {
;       int tok = td.bcol + bj * 128 + n * 16 + br_l;
;       int pos = tok & (SEQ - 1);
;       #pragma unroll
;       for (int m = 0; m < 4; ++m) {
;         int i0 = m * 16 + ar_l;
;         const float4* cs = (const float4*)(td.aux + ((long)pos * 128 + i0) * 2);
;         float4 c01 = cs[0], c23 = cs[1];
;         float cc[4] = {c01.x, c01.z, c23.x, c23.z}, ss[4] = {c01.y, c01.w, c23.y, c23.w};
;         f32x4 t1 = acc[0][bj][m][n], t2 = acc[1][bj][m][n], o1, o2;
;         #pragma unroll
;         for (int j = 0; j < 4; ++j) { o1[j] = (t1[j] * cc[j] - t2[j] * ss[j]) * sc; o2[j] = (t2[j] * cc[j] + t1[j] * ss[j]) * sc; }
;         long o = (long)tok * td.ldo + (td.brow + i0);
;         uint2 pk; pk.x = pack2(o1[0], o1[1]); pk.y = pack2(o1[2], o1[3]);
;         *(uint2*)(td.outb + o) = pk;
;         pk.x = pack2(o2[0], o2[1]); pk.y = pack2(o2[2], o2[3]);
;         *(uint2*)(td.outb + o + 128) = pk;
;         if (td.outT) {
;           u16* tp = td.outT + (long)i0 * LDT + tok;
;           #pragma unroll
;           for (int j = 0; j < 4; ++j) {
;             tp[(long)j * LDT] = (u16)(pack2(o1[j], 0.f) & 0xffffu);
;             tp[(long)(j + 128) * LDT] = (u16)(pack2(o2[j], 0.f) & 0xffffu);
;           }
;         }
;       }
;     }
.LBB0_585:
	s_andn2_b64 vcc, exec, s[46:47]
	s_cbranch_vccnz .LBB0_618
	v_mbcnt_lo_u32_b32 v252, -1, 0
	v_mbcnt_hi_u32_b32 v252, -1, v252
	v_and_b32_e32 v252, 16, v252
	v_lshrrev_b32_e32 v253, 1, v252
	v_add_u32_e32 v252, v252, v253
	v_mov_b32_e32 v253, 0
	v_or_b32_e32 v128, s50, v164
	v_lshlrev_b32_e32 v129, 7, v128
	v_and_b32_e32 v156, 0x7b780, v129
	v_add_u32_e32 v132, v156, v136
	v_lshl_add_u64 v[130:131], v[132:133], 3, s[40:41]
	v_mov_b32_e32 v236, v130
	v_mov_b32_e32 v237, v131
	v_add_co_u32_e32 v238, vcc, 0x4000, v130
	s_nop 1
	v_addc_co_u32_e32 v239, vcc, 0, v131, vcc
	v_add_co_u32_e32 v240, vcc, 0x20000, v130
	s_nop 1
	v_addc_co_u32_e32 v241, vcc, 0, v131, vcc
	v_add_co_u32_e32 v242, vcc, 0x24000, v130
	s_nop 1
	v_addc_co_u32_e32 v243, vcc, 0, v131, vcc
	global_load_dwordx4 v[172:175], v[236:237], off
	global_load_dwordx4 v[176:179], v[236:237], off offset:16
	global_load_dwordx4 v[180:183], v[236:237], off offset:128
	global_load_dwordx4 v[184:187], v[236:237], off offset:144
	global_load_dwordx4 v[188:191], v[236:237], off offset:256
	global_load_dwordx4 v[192:195], v[236:237], off offset:272
	global_load_dwordx4 v[196:199], v[236:237], off offset:384
	global_load_dwordx4 v[200:203], v[236:237], off offset:400
	global_load_dwordx4 v[204:207], v[238:239], off
	global_load_dwordx4 v[208:211], v[238:239], off offset:16
	global_load_dwordx4 v[212:215], v[238:239], off offset:128
	global_load_dwordx4 v[216:219], v[238:239], off offset:144
	global_load_dwordx4 v[220:223], v[238:239], off offset:256
	global_load_dwordx4 v[224:227], v[238:239], off offset:272
	global_load_dwordx4 v[228:231], v[238:239], off offset:384
	global_load_dwordx4 v[232:235], v[238:239], off offset:400
	v_ashrrev_i32_e32 v129, 31, v128
	v_mul_lo_u32 v132, s35, v128
	v_mad_u64_u32 v[146:147], s[0:1], s34, v128, 0
	v_mul_lo_u32 v135, s34, v129
	v_add_u32_e32 v130, s14, v136
	v_add3_u32 v147, v147, v135, v132
	v_ashrrev_i32_e32 v131, 31, v130
	v_lshl_add_u64 v[146:147], v[146:147], 1, s[36:37]
	v_lshl_add_u64 v[148:149], v[130:131], 1, v[146:147]
	v_mov_b32_e32 v137, v133
	s_cmp_lg_u64 s[42:43], 0
	v_lshlrev_b64 v[150:151], 15, v[136:137]
	s_cselect_b64 s[4:5], -1, 0
	s_cmp_eq_u64 s[42:43], 0
	s_waitcnt vmcnt(14)
	v_mov_b32_e32 v138, v172
	v_mov_b32_e32 v139, v173
	v_mov_b32_e32 v140, v174
	v_mov_b32_e32 v141, v175
	v_mov_b32_e32 v142, v176
	v_mov_b32_e32 v143, v177
	v_mov_b32_e32 v144, v178
	v_mov_b32_e32 v145, v179
	v_mov_b32_e32 v147, v140
	v_mov_b32_e32 v140, v139
	v_mov_b32_e32 v139, v144
	v_mov_b32_e32 v144, v143
	v_mov_b32_e32 v146, v138
	v_mov_b32_e32 v138, v142
	v_pk_mul_f32 v[142:143], v[124:125], v[140:141]
	v_pk_mul_f32 v[140:141], v[60:61], v[140:141]
	v_pk_mul_f32 v[152:153], v[126:127], v[144:145]
	v_pk_mul_f32 v[144:145], v[62:63], v[144:145]
	v_pk_fma_f32 v[142:143], v[60:61], v[146:147], v[142:143]
	v_pk_fma_f32 v[140:141], v[124:125], v[146:147], v[140:141] neg_lo:[0,0,1] neg_hi:[0,0,1]
	v_pk_fma_f32 v[152:153], v[62:63], v[138:139], v[152:153]
	v_pk_fma_f32 v[138:139], v[126:127], v[138:139], v[144:145] neg_lo:[0,0,1] neg_hi:[0,0,1]
	v_pk_mul_f32 v[144:145], v[134:135], v[142:143] op_sel_hi:[0,1]
	v_pk_mul_f32 v[146:147], v[134:135], v[140:141] op_sel_hi:[0,1]
	v_pk_mul_f32 v[142:143], v[134:135], v[138:139] op_sel_hi:[0,1]
	v_pk_mul_f32 v[140:141], v[134:135], v[152:153] op_sel_hi:[0,1]
	v_cvt_pk_bf16_f32 v138, v146, v147
	v_cvt_pk_bf16_f32 v139, v142, v143
	v_cvt_pk_bf16_f32 v152, v144, v145
	v_cvt_pk_bf16_f32 v153, v140, v141
	v_mov_b32_e32 v244, v138
	v_mov_b32_e32 v245, v139
	v_mov_b32_e32 v248, v152
	v_mov_b32_e32 v249, v153
	v_lshl_add_u64 v[138:139], s[42:43], 0, v[150:151]
	s_cbranch_scc1 .LBB0_588
	v_lshl_add_u64 v[150:151], v[128:129], 1, v[138:139]
	v_add_co_u32_e32 v152, vcc, 0x400000, v150
	v_cvt_pk_bf16_f32 v132, v146, s0
	s_nop 0
	v_addc_co_u32_e32 v153, vcc, 0, v151, vcc
	global_store_short v[150:151], v132, off
	v_cvt_pk_bf16_f32 v132, v144, s0
	v_add_co_u32_e32 v146, vcc, 0x8000, v150
	global_store_short v[152:153], v132, off
	v_cvt_pk_bf16_f32 v132, v147, s0
	v_addc_co_u32_e32 v147, vcc, 0, v151, vcc
	v_add_co_u32_e32 v144, vcc, 0x408000, v150
	global_store_short v[146:147], v132, off
	v_cvt_pk_bf16_f32 v132, v145, s0
	v_addc_co_u32_e32 v145, vcc, 0, v151, vcc
	global_store_short v[144:145], v132, off
	v_add_co_u32_e32 v144, vcc, s66, v150
	v_cvt_pk_bf16_f32 v132, v142, s0
	s_nop 0
	v_addc_co_u32_e32 v145, vcc, 0, v151, vcc
	global_store_short v[144:145], v132, off
	v_add_co_u32_e32 v144, vcc, 0x410000, v150
	v_cvt_pk_bf16_f32 v132, v140, s0
	s_nop 0
	v_addc_co_u32_e32 v145, vcc, 0, v151, vcc
	v_add_co_u32_e32 v142, vcc, 0x18000, v150
	global_store_short v[144:145], v132, off
	v_cvt_pk_bf16_f32 v132, v143, s0
	v_addc_co_u32_e32 v143, vcc, 0, v151, vcc
	v_add_co_u32_e32 v140, vcc, 0x418000, v150
	global_store_short v[142:143], v132, off
	v_cvt_pk_bf16_f32 v132, v141, s0
	v_addc_co_u32_e32 v141, vcc, 0, v151, vcc
	global_store_short v[140:141], v132, off
; __device__ __forceinline__ void gemm_tile(const TileDesc& td, char* shm_c, const int wv) {
;     ...
;   } else if (mode == EPI_ROPE_A) {
;     const float sc = td.scale;
;     #pragma unroll
;     for (int bj = 0; bj < 2; ++bj)
;     #pragma unroll
;     for (int n = 0; n < 2; ++n) {
;       int tok = td.bcol + bj * 128 + n * 16 + br_l;
;       int pos = tok & (SEQ - 1);
;       #pragma unroll
;       for (int m = 0; m < 4; ++m) {
;         int i0 = m * 16 + ar_l;
;         const float4* cs = (const float4*)(td.aux + ((long)pos * 128 + i0) * 2);
;         float4 c01 = cs[0], c23 = cs[1];
;         float cc[4] = {c01.x, c01.z, c23.x, c23.z}, ss[4] = {c01.y, c01.w, c23.y, c23.w};
;         f32x4 t1 = acc[0][bj][m][n], t2 = acc[1][bj][m][n], o1, o2;
;         #pragma unroll
;         for (int j = 0; j < 4; ++j) { o1[j] = (t1[j] * cc[j] - t2[j] * ss[j]) * sc; o2[j] = (t2[j] * cc[j] + t1[j] * ss[j]) * sc; }
;         long o = (long)tok * td.ldo + (td.brow + i0);
;         uint2 pk; pk.x = pack2(o1[0], o1[1]); pk.y = pack2(o1[2], o1[3]);
;         *(uint2*)(td.outb + o) = pk;
;         pk.x = pack2(o2[0], o2[1]); pk.y = pack2(o2[2], o2[3]);
;         *(uint2*)(td.outb + o + 128) = pk;
;         if (td.outT) {
;           u16* tp = td.outT + (long)i0 * LDT + tok;
;           #pragma unroll
;           for (int j = 0; j < 4; ++j) {
;             tp[(long)j * LDT] = (u16)(pack2(o1[j], 0.f) & 0xffffu);
;             tp[(long)(j + 128) * LDT] = (u16)(pack2(o2[j], 0.f) & 0xffffu);
;           }
;         }
;       }
;     }
.LBB0_588:
	v_or_b32_e32 v132, 16, v136
	v_add_u32_e32 v140, v156, v132
	v_mov_b32_e32 v141, v133
	v_lshl_add_u64 v[144:145], v[140:141], 3, s[40:41]
	s_nop 0
	v_mov_b32_e32 v135, v134
	v_cndmask_b32_e64 v137, 0, 1, s[4:5]
	v_lshlrev_b64 v[152:153], 15, v[132:133]
	v_cmp_ne_u32_e64 s[0:1], 1, v137
	s_andn2_b64 vcc, exec, s[4:5]
	s_waitcnt vmcnt(12)
	v_mov_b32_e32 v140, v180
	v_mov_b32_e32 v141, v181
	v_mov_b32_e32 v142, v182
	v_mov_b32_e32 v143, v183
	v_mov_b32_e32 v144, v184
	v_mov_b32_e32 v145, v185
	v_mov_b32_e32 v146, v186
	v_mov_b32_e32 v147, v187
	v_mov_b32_e32 v151, v142
	v_mov_b32_e32 v142, v141
	v_mov_b32_e32 v141, v146
	v_mov_b32_e32 v146, v145
	v_mov_b32_e32 v150, v140
	v_mov_b32_e32 v140, v144
	v_pk_mul_f32 v[144:145], v[116:117], v[142:143]
	v_pk_mul_f32 v[142:143], v[52:53], v[142:143]
	v_pk_mul_f32 v[154:155], v[118:119], v[146:147]
	v_pk_mul_f32 v[146:147], v[54:55], v[146:147]
	v_pk_fma_f32 v[144:145], v[52:53], v[150:151], v[144:145]
	v_pk_fma_f32 v[142:143], v[116:117], v[150:151], v[142:143] neg_lo:[0,0,1] neg_hi:[0,0,1]
	v_pk_fma_f32 v[154:155], v[54:55], v[140:141], v[154:155]
	v_pk_fma_f32 v[140:141], v[118:119], v[140:141], v[146:147] neg_lo:[0,0,1] neg_hi:[0,0,1]
	v_pk_mul_f32 v[146:147], v[134:135], v[144:145]
	v_pk_mul_f32 v[150:151], v[134:135], v[142:143]
	v_pk_mul_f32 v[144:145], v[134:135], v[140:141]
	v_pk_mul_f32 v[142:143], v[134:135], v[154:155]
	v_cvt_pk_bf16_f32 v140, v150, v151
	v_cvt_pk_bf16_f32 v141, v144, v145
	v_cvt_pk_bf16_f32 v154, v146, v147
	v_cvt_pk_bf16_f32 v155, v142, v143
	v_mov_b32_e32 v246, v140
	v_mov_b32_e32 v247, v141
	v_mov_b32_e32 v250, v154
	v_mov_b32_e32 v251, v155
	v_lshl_add_u64 v[170:171], v[148:149], 0, v[252:253]
	s_nop 0
	v_permlane16_swap_b32_e32 v244, v246
	v_permlane16_swap_b32_e32 v245, v247
	v_permlane16_swap_b32_e32 v248, v250
	v_permlane16_swap_b32_e32 v249, v251
	global_store_dwordx4 v[170:171], v[244:247], off
	global_store_dwordx4 v[170:171], v[248:251], off offset:256
	v_lshl_add_u64 v[140:141], s[42:43], 0, v[152:153]
	s_cbranch_vccnz .LBB0_590
	v_lshl_add_u64 v[152:153], v[128:129], 1, v[140:141]
	v_add_co_u32_e32 v154, vcc, 0x400000, v152
	v_cvt_pk_bf16_f32 v137, v150, s0
	s_nop 0
	v_addc_co_u32_e32 v155, vcc, 0, v153, vcc
	global_store_short v[152:153], v137, off
	v_cvt_pk_bf16_f32 v137, v146, s0
	v_add_co_u32_e32 v150, vcc, 0x8000, v152
	global_store_short v[154:155], v137, off
	v_cvt_pk_bf16_f32 v137, v151, s0
	v_addc_co_u32_e32 v151, vcc, 0, v153, vcc
	v_add_co_u32_e32 v146, vcc, 0x408000, v152
	global_store_short v[150:151], v137, off
	v_cvt_pk_bf16_f32 v137, v147, s0
	v_addc_co_u32_e32 v147, vcc, 0, v153, vcc
	global_store_short v[146:147], v137, off
	v_add_co_u32_e32 v146, vcc, s66, v152
	v_cvt_pk_bf16_f32 v137, v144, s0
	s_nop 0
	v_addc_co_u32_e32 v147, vcc, 0, v153, vcc
	global_store_short v[146:147], v137, off
	v_add_co_u32_e32 v146, vcc, 0x410000, v152
	v_cvt_pk_bf16_f32 v137, v142, s0
	s_nop 0
	v_addc_co_u32_e32 v147, vcc, 0, v153, vcc
	v_add_co_u32_e32 v144, vcc, 0x18000, v152
	global_store_short v[146:147], v137, off
	v_cvt_pk_bf16_f32 v137, v145, s0
	v_addc_co_u32_e32 v145, vcc, 0, v153, vcc
	v_add_co_u32_e32 v142, vcc, 0x418000, v152
	global_store_short v[144:145], v137, off
	v_cvt_pk_bf16_f32 v137, v143, s0
	v_addc_co_u32_e32 v143, vcc, 0, v153, vcc
	global_store_short v[142:143], v137, off
.LBB0_590:
	v_or_b32_e32 v142, 32, v136
	v_add_u32_e32 v144, v156, v142
	v_mov_b32_e32 v145, v133
	v_lshl_add_u64 v[150:151], v[144:145], 3, s[40:41]
	s_nop 0
	v_mov_b32_e32 v143, v133
	v_lshlrev_b64 v[158:159], 15, v[142:143]
	s_and_b64 vcc, exec, s[0:1]
	s_waitcnt vmcnt(12)
	v_mov_b32_e32 v144, v188
	v_mov_b32_e32 v145, v189
	v_mov_b32_e32 v146, v190
	v_mov_b32_e32 v147, v191
	v_mov_b32_e32 v150, v192
	v_mov_b32_e32 v151, v193
	v_mov_b32_e32 v152, v194
	v_mov_b32_e32 v153, v195
	v_mov_b32_e32 v155, v146
	v_mov_b32_e32 v146, v145
	v_mov_b32_e32 v145, v152
	v_mov_b32_e32 v152, v151
	v_mov_b32_e32 v154, v144
	v_mov_b32_e32 v144, v150
	v_pk_mul_f32 v[150:151], v[108:109], v[146:147]
	v_pk_mul_f32 v[146:147], v[44:45], v[146:147]
	v_pk_mul_f32 v[166:167], v[110:111], v[152:153]
	v_pk_mul_f32 v[152:153], v[46:47], v[152:153]
	v_pk_fma_f32 v[150:151], v[44:45], v[154:155], v[150:151]
	v_pk_fma_f32 v[146:147], v[108:109], v[154:155], v[146:147] neg_lo:[0,0,1] neg_hi:[0,0,1]
	v_pk_fma_f32 v[166:167], v[46:47], v[144:145], v[166:167]
	v_pk_fma_f32 v[144:145], v[110:111], v[144:145], v[152:153] neg_lo:[0,0,1] neg_hi:[0,0,1]
	v_pk_mul_f32 v[152:153], v[134:135], v[150:151]
	v_pk_mul_f32 v[154:155], v[134:135], v[146:147]
	v_pk_mul_f32 v[150:151], v[134:135], v[144:145]
	v_pk_mul_f32 v[146:147], v[134:135], v[166:167]
	v_cvt_pk_bf16_f32 v144, v154, v155
	v_cvt_pk_bf16_f32 v145, v150, v151
	v_cvt_pk_bf16_f32 v166, v152, v153
	v_cvt_pk_bf16_f32 v167, v146, v147
	v_mov_b32_e32 v244, v144
	v_mov_b32_e32 v245, v145
	v_mov_b32_e32 v248, v166
	v_mov_b32_e32 v249, v167
	v_lshl_add_u64 v[144:145], s[42:43], 0, v[158:159]
	s_cbranch_vccnz .LBB0_592
	v_lshl_add_u64 v[158:159], v[128:129], 1, v[144:145]
	v_add_co_u32_e32 v166, vcc, 0x400000, v158
	v_cvt_pk_bf16_f32 v137, v154, s0
	s_nop 0
	v_addc_co_u32_e32 v167, vcc, 0, v159, vcc
	global_store_short v[158:159], v137, off
	v_cvt_pk_bf16_f32 v137, v152, s0
	v_add_co_u32_e32 v154, vcc, 0x8000, v158
	global_store_short v[166:167], v137, off
	v_cvt_pk_bf16_f32 v137, v155, s0
	v_addc_co_u32_e32 v155, vcc, 0, v159, vcc
	v_add_co_u32_e32 v152, vcc, 0x408000, v158
	global_store_short v[154:155], v137, off
	v_cvt_pk_bf16_f32 v137, v153, s0
	v_addc_co_u32_e32 v153, vcc, 0, v159, vcc
	global_store_short v[152:153], v137, off
	v_add_co_u32_e32 v152, vcc, s66, v158
	v_cvt_pk_bf16_f32 v137, v150, s0
	s_nop 0
	v_addc_co_u32_e32 v153, vcc, 0, v159, vcc
	global_store_short v[152:153], v137, off
	v_add_co_u32_e32 v152, vcc, 0x410000, v158
	v_cvt_pk_bf16_f32 v137, v146, s0
	s_nop 0
	v_addc_co_u32_e32 v153, vcc, 0, v159, vcc
	v_add_co_u32_e32 v150, vcc, 0x18000, v158
	global_store_short v[152:153], v137, off
	v_cvt_pk_bf16_f32 v137, v151, s0
	v_addc_co_u32_e32 v151, vcc, 0, v159, vcc
	v_add_co_u32_e32 v146, vcc, 0x418000, v158
	global_store_short v[150:151], v137, off
	v_cvt_pk_bf16_f32 v137, v147, s0
	v_addc_co_u32_e32 v147, vcc, 0, v159, vcc
	global_store_short v[146:147], v137, off
; __device__ __forceinline__ void gemm_tile(const TileDesc& td, char* shm_c, const int wv) {
;     ...
;   } else if (mode == EPI_ROPE_A) {
;     const float sc = td.scale;
;     #pragma unroll
;     for (int bj = 0; bj < 2; ++bj)
;     #pragma unroll
;     for (int n = 0; n < 2; ++n) {
;       int tok = td.bcol + bj * 128 + n * 16 + br_l;
;       int pos = tok & (SEQ - 1);
;       #pragma unroll
;       for (int m = 0; m < 4; ++m) {
;         int i0 = m * 16 + ar_l;
;         const float4* cs = (const float4*)(td.aux + ((long)pos * 128 + i0) * 2);
;         float4 c01 = cs[0], c23 = cs[1];
;         float cc[4] = {c01.x, c01.z, c23.x, c23.z}, ss[4] = {c01.y, c01.w, c23.y, c23.w};
;         f32x4 t1 = acc[0][bj][m][n], t2 = acc[1][bj][m][n], o1, o2;
;         #pragma unroll
;         for (int j = 0; j < 4; ++j) { o1[j] = (t1[j] * cc[j] - t2[j] * ss[j]) * sc; o2[j] = (t2[j] * cc[j] + t1[j] * ss[j]) * sc; }
;         long o = (long)tok * td.ldo + (td.brow + i0);
;         uint2 pk; pk.x = pack2(o1[0], o1[1]); pk.y = pack2(o1[2], o1[3]);
;         *(uint2*)(td.outb + o) = pk;
;         pk.x = pack2(o2[0], o2[1]); pk.y = pack2(o2[2], o2[3]);
;         *(uint2*)(td.outb + o + 128) = pk;
;         if (td.outT) {
;           u16* tp = td.outT + (long)i0 * LDT + tok;
;           #pragma unroll
;           for (int j = 0; j < 4; ++j) {
;             tp[(long)j * LDT] = (u16)(pack2(o1[j], 0.f) & 0xffffu);
;             tp[(long)(j + 128) * LDT] = (u16)(pack2(o2[j], 0.f) & 0xffffu);
;           }
;         }
;       }
;     }
.LBB0_592:
	v_or_b32_e32 v146, 48, v136
	v_add_u32_e32 v150, v156, v146
	v_mov_b32_e32 v151, v133
	v_lshl_add_u64 v[154:155], v[150:151], 3, s[40:41]
	s_nop 0
	v_mov_b32_e32 v147, v133
	v_lshlrev_b64 v[158:159], 15, v[146:147]
	s_and_b64 vcc, exec, s[0:1]
	s_waitcnt vmcnt(10)
	v_mov_b32_e32 v150, v196
	v_mov_b32_e32 v151, v197
	v_mov_b32_e32 v152, v198
	v_mov_b32_e32 v153, v199
	v_mov_b32_e32 v154, v200
	v_mov_b32_e32 v155, v201
	v_mov_b32_e32 v156, v202
	v_mov_b32_e32 v157, v203
	v_mov_b32_e32 v167, v152
	v_mov_b32_e32 v152, v151
	v_mov_b32_e32 v151, v156
	v_mov_b32_e32 v156, v155
	v_mov_b32_e32 v166, v150
	v_mov_b32_e32 v150, v154
	v_pk_mul_f32 v[154:155], v[100:101], v[152:153]
	v_pk_mul_f32 v[152:153], v[36:37], v[152:153]
	v_pk_mul_f32 v[168:169], v[102:103], v[156:157]
	v_pk_mul_f32 v[156:157], v[38:39], v[156:157]
	v_pk_fma_f32 v[154:155], v[36:37], v[166:167], v[154:155]
	v_pk_fma_f32 v[152:153], v[100:101], v[166:167], v[152:153] neg_lo:[0,0,1] neg_hi:[0,0,1]
	v_pk_fma_f32 v[166:167], v[38:39], v[150:151], v[168:169]
	v_pk_fma_f32 v[168:169], v[102:103], v[150:151], v[156:157] neg_lo:[0,0,1] neg_hi:[0,0,1]
	v_pk_mul_f32 v[156:157], v[134:135], v[152:153]
	v_pk_mul_f32 v[152:153], v[134:135], v[168:169]
	v_pk_mul_f32 v[154:155], v[134:135], v[154:155]
	v_pk_mul_f32 v[150:151], v[134:135], v[166:167]
	v_cvt_pk_bf16_f32 v166, v156, v157
	v_cvt_pk_bf16_f32 v167, v152, v153
	v_cvt_pk_bf16_f32 v168, v154, v155
	v_cvt_pk_bf16_f32 v169, v150, v151
	v_mov_b32_e32 v246, v166
	v_mov_b32_e32 v247, v167
	v_mov_b32_e32 v250, v168
	v_mov_b32_e32 v251, v169
	v_lshl_add_u64 v[170:171], v[148:149], 0, v[252:253]
	s_nop 0
	v_permlane16_swap_b32_e32 v244, v246
	v_permlane16_swap_b32_e32 v245, v247
	v_permlane16_swap_b32_e32 v248, v250
	v_permlane16_swap_b32_e32 v249, v251
	global_store_dwordx4 v[170:171], v[244:247], off offset:64
	global_store_dwordx4 v[170:171], v[248:251], off offset:320
	v_lshl_add_u64 v[148:149], s[42:43], 0, v[158:159]
	s_cbranch_vccnz .LBB0_594
	v_lshl_add_u64 v[158:159], v[128:129], 1, v[148:149]
	v_add_co_u32_e32 v166, vcc, 0x400000, v158
	v_cvt_pk_bf16_f32 v137, v156, s0
	s_nop 0
	v_addc_co_u32_e32 v167, vcc, 0, v159, vcc
	global_store_short v[158:159], v137, off
	v_cvt_pk_bf16_f32 v137, v154, s0
	v_add_co_u32_e32 v156, vcc, 0x8000, v158
	global_store_short v[166:167], v137, off
	v_cvt_pk_bf16_f32 v137, v157, s0
	v_addc_co_u32_e32 v157, vcc, 0, v159, vcc
	v_add_co_u32_e32 v154, vcc, 0x408000, v158
	global_store_short v[156:157], v137, off
	v_cvt_pk_bf16_f32 v137, v155, s0
	v_addc_co_u32_e32 v155, vcc, 0, v159, vcc
	global_store_short v[154:155], v137, off
	v_add_co_u32_e32 v154, vcc, s66, v158
	v_cvt_pk_bf16_f32 v137, v152, s0
	s_nop 0
	v_addc_co_u32_e32 v155, vcc, 0, v159, vcc
	global_store_short v[154:155], v137, off
	v_add_co_u32_e32 v154, vcc, 0x410000, v158
	v_cvt_pk_bf16_f32 v137, v150, s0
	s_nop 0
	v_addc_co_u32_e32 v155, vcc, 0, v159, vcc
	v_add_co_u32_e32 v152, vcc, 0x18000, v158
	global_store_short v[154:155], v137, off
	v_cvt_pk_bf16_f32 v137, v153, s0
	v_addc_co_u32_e32 v153, vcc, 0, v159, vcc
	v_add_co_u32_e32 v150, vcc, 0x418000, v158
	global_store_short v[152:153], v137, off
	v_cvt_pk_bf16_f32 v137, v151, s0
	v_addc_co_u32_e32 v151, vcc, 0, v159, vcc
	global_store_short v[150:151], v137, off
.LBB0_594:
	v_or_b32_e32 v147, 16, v128
	v_lshlrev_b32_e32 v137, 7, v147
	v_and_b32_e32 v143, 0x7ff80, v137
	v_add_u32_e32 v150, v143, v136
	v_mov_b32_e32 v151, v133
	v_lshl_add_u64 v[150:151], v[150:151], 3, s[40:41]
	v_mul_lo_u32 v137, s34, v129
	v_mul_lo_u32 v165, s35, v147
	v_mad_u64_u32 v[150:151], s[2:3], s34, v147, 0
	v_add3_u32 v151, v151, v137, v165
	v_lshl_add_u64 v[150:151], v[150:151], 1, s[36:37]
	s_and_b64 vcc, exec, s[0:1]
	v_lshl_add_u64 v[150:151], v[130:131], 1, v[150:151]
	s_waitcnt vmcnt(10)
	v_mov_b32_e32 v152, v204
	v_mov_b32_e32 v153, v205
	v_mov_b32_e32 v154, v206
	v_mov_b32_e32 v155, v207
	v_mov_b32_e32 v156, v208
	v_mov_b32_e32 v157, v209
	v_mov_b32_e32 v158, v210
	v_mov_b32_e32 v159, v211
	v_mov_b32_e32 v167, v154
	v_mov_b32_e32 v154, v153
	v_mov_b32_e32 v153, v158
	v_mov_b32_e32 v158, v157
	v_mov_b32_e32 v166, v152
	v_mov_b32_e32 v152, v156
	v_pk_mul_f32 v[156:157], v[120:121], v[154:155]
	v_pk_mul_f32 v[154:155], v[56:57], v[154:155]
	v_pk_mul_f32 v[168:169], v[122:123], v[158:159]
	v_pk_mul_f32 v[158:159], v[58:59], v[158:159]
	v_pk_fma_f32 v[156:157], v[56:57], v[166:167], v[156:157]
	v_pk_fma_f32 v[154:155], v[120:121], v[166:167], v[154:155] neg_lo:[0,0,1] neg_hi:[0,0,1]
	v_pk_fma_f32 v[166:167], v[58:59], v[152:153], v[168:169]
	v_pk_fma_f32 v[168:169], v[122:123], v[152:153], v[158:159] neg_lo:[0,0,1] neg_hi:[0,0,1]
	v_pk_mul_f32 v[158:159], v[134:135], v[154:155]
	v_pk_mul_f32 v[154:155], v[134:135], v[168:169]
	v_pk_mul_f32 v[156:157], v[134:135], v[156:157]
	v_pk_mul_f32 v[152:153], v[134:135], v[166:167]
	v_cvt_pk_bf16_f32 v166, v158, v159
	v_cvt_pk_bf16_f32 v167, v154, v155
	v_cvt_pk_bf16_f32 v168, v156, v157
	v_cvt_pk_bf16_f32 v169, v152, v153
	v_mov_b32_e32 v244, v166
	v_mov_b32_e32 v245, v167
	v_mov_b32_e32 v248, v168
	v_mov_b32_e32 v249, v169
	s_cbranch_vccnz .LBB0_596
	v_lshl_add_u64 v[166:167], v[128:129], 1, v[138:139]
	v_add_co_u32_e32 v168, vcc, 0x400000, v166
	v_cvt_pk_bf16_f32 v147, v158, s0
	s_nop 0
	v_addc_co_u32_e32 v169, vcc, 0, v167, vcc
	global_store_short v[166:167], v147, off offset:32
	v_cvt_pk_bf16_f32 v147, v156, s0
	v_add_co_u32_e32 v158, vcc, 0x8000, v166
	global_store_short v[168:169], v147, off offset:32
	v_cvt_pk_bf16_f32 v147, v159, s0
	v_addc_co_u32_e32 v159, vcc, 0, v167, vcc
	v_add_co_u32_e32 v156, vcc, 0x408000, v166
	global_store_short v[158:159], v147, off offset:32
	v_cvt_pk_bf16_f32 v147, v157, s0
	v_addc_co_u32_e32 v157, vcc, 0, v167, vcc
	global_store_short v[156:157], v147, off offset:32
	v_add_co_u32_e32 v156, vcc, s66, v166
	v_cvt_pk_bf16_f32 v147, v154, s0
	s_nop 0
	v_addc_co_u32_e32 v157, vcc, 0, v167, vcc
	global_store_short v[156:157], v147, off offset:32
	v_add_co_u32_e32 v156, vcc, 0x410000, v166
	v_cvt_pk_bf16_f32 v147, v152, s0
	s_nop 0
	v_addc_co_u32_e32 v157, vcc, 0, v167, vcc
	v_add_co_u32_e32 v154, vcc, 0x18000, v166
	global_store_short v[156:157], v147, off offset:32
	v_cvt_pk_bf16_f32 v147, v155, s0
	v_addc_co_u32_e32 v155, vcc, 0, v167, vcc
	v_add_co_u32_e32 v152, vcc, 0x418000, v166
	global_store_short v[154:155], v147, off offset:32
	v_cvt_pk_bf16_f32 v147, v153, s0
	v_addc_co_u32_e32 v153, vcc, 0, v167, vcc
	global_store_short v[152:153], v147, off offset:32
; __device__ __forceinline__ void gemm_tile(const TileDesc& td, char* shm_c, const int wv) {
;     ...
;   } else if (mode == EPI_ROPE_A) {
;     const float sc = td.scale;
;     #pragma unroll
;     for (int bj = 0; bj < 2; ++bj)
;     #pragma unroll
;     for (int n = 0; n < 2; ++n) {
;       int tok = td.bcol + bj * 128 + n * 16 + br_l;
;       int pos = tok & (SEQ - 1);
;       #pragma unroll
;       for (int m = 0; m < 4; ++m) {
;         int i0 = m * 16 + ar_l;
;         const float4* cs = (const float4*)(td.aux + ((long)pos * 128 + i0) * 2);
;         float4 c01 = cs[0], c23 = cs[1];
;         float cc[4] = {c01.x, c01.z, c23.x, c23.z}, ss[4] = {c01.y, c01.w, c23.y, c23.w};
;         f32x4 t1 = acc[0][bj][m][n], t2 = acc[1][bj][m][n], o1, o2;
;         #pragma unroll
;         for (int j = 0; j < 4; ++j) { o1[j] = (t1[j] * cc[j] - t2[j] * ss[j]) * sc; o2[j] = (t2[j] * cc[j] + t1[j] * ss[j]) * sc; }
;         long o = (long)tok * td.ldo + (td.brow + i0);
;         uint2 pk; pk.x = pack2(o1[0], o1[1]); pk.y = pack2(o1[2], o1[3]);
;         *(uint2*)(td.outb + o) = pk;
;         pk.x = pack2(o2[0], o2[1]); pk.y = pack2(o2[2], o2[3]);
;         *(uint2*)(td.outb + o + 128) = pk;
;         if (td.outT) {
;           u16* tp = td.outT + (long)i0 * LDT + tok;
;           #pragma unroll
;           for (int j = 0; j < 4; ++j) {
;             tp[(long)j * LDT] = (u16)(pack2(o1[j], 0.f) & 0xffffu);
;             tp[(long)(j + 128) * LDT] = (u16)(pack2(o2[j], 0.f) & 0xffffu);
;           }
;         }
;       }
;     }
.LBB0_596:
	v_add_u32_e32 v152, v143, v132
	v_mov_b32_e32 v153, v133
	v_lshl_add_u64 v[156:157], v[152:153], 3, s[40:41]
	s_nop 0
	s_and_b64 vcc, exec, s[0:1]
	s_waitcnt vmcnt(8)
	v_mov_b32_e32 v152, v212
	v_mov_b32_e32 v153, v213
	v_mov_b32_e32 v154, v214
	v_mov_b32_e32 v155, v215
	v_mov_b32_e32 v156, v216
	v_mov_b32_e32 v157, v217
	v_mov_b32_e32 v158, v218
	v_mov_b32_e32 v159, v219
	v_mov_b32_e32 v167, v154
	v_mov_b32_e32 v154, v153
	v_mov_b32_e32 v153, v158
	v_mov_b32_e32 v158, v157
	v_mov_b32_e32 v166, v152
	v_mov_b32_e32 v152, v156
	v_pk_mul_f32 v[156:157], v[112:113], v[154:155]
	v_pk_mul_f32 v[154:155], v[48:49], v[154:155]
	v_pk_mul_f32 v[168:169], v[114:115], v[158:159]
	v_pk_mul_f32 v[158:159], v[50:51], v[158:159]
	v_pk_fma_f32 v[156:157], v[48:49], v[166:167], v[156:157]
	v_pk_fma_f32 v[154:155], v[112:113], v[166:167], v[154:155] neg_lo:[0,0,1] neg_hi:[0,0,1]
	v_pk_fma_f32 v[166:167], v[50:51], v[152:153], v[168:169]
	v_pk_fma_f32 v[168:169], v[114:115], v[152:153], v[158:159] neg_lo:[0,0,1] neg_hi:[0,0,1]
	v_pk_mul_f32 v[158:159], v[134:135], v[154:155]
	v_pk_mul_f32 v[154:155], v[134:135], v[168:169]
	v_pk_mul_f32 v[156:157], v[134:135], v[156:157]
	v_pk_mul_f32 v[152:153], v[134:135], v[166:167]
	v_cvt_pk_bf16_f32 v166, v158, v159
	v_cvt_pk_bf16_f32 v167, v154, v155
	v_cvt_pk_bf16_f32 v168, v156, v157
	v_cvt_pk_bf16_f32 v169, v152, v153
	v_mov_b32_e32 v246, v166
	v_mov_b32_e32 v247, v167
	v_mov_b32_e32 v250, v168
	v_mov_b32_e32 v251, v169
	v_lshl_add_u64 v[170:171], v[150:151], 0, v[252:253]
	s_nop 0
	v_permlane16_swap_b32_e32 v244, v246
	v_permlane16_swap_b32_e32 v245, v247
	v_permlane16_swap_b32_e32 v248, v250
	v_permlane16_swap_b32_e32 v249, v251
	global_store_dwordx4 v[170:171], v[244:247], off
	global_store_dwordx4 v[170:171], v[248:251], off offset:256
	s_cbranch_vccnz .LBB0_598
	v_lshl_add_u64 v[166:167], v[128:129], 1, v[140:141]
	v_add_co_u32_e32 v168, vcc, 0x400000, v166
	v_cvt_pk_bf16_f32 v147, v158, s0
	s_nop 0
	v_addc_co_u32_e32 v169, vcc, 0, v167, vcc
	global_store_short v[166:167], v147, off offset:32
	v_cvt_pk_bf16_f32 v147, v156, s0
	v_add_co_u32_e32 v158, vcc, 0x8000, v166
	global_store_short v[168:169], v147, off offset:32
	v_cvt_pk_bf16_f32 v147, v159, s0
	v_addc_co_u32_e32 v159, vcc, 0, v167, vcc
	v_add_co_u32_e32 v156, vcc, 0x408000, v166
	global_store_short v[158:159], v147, off offset:32
	v_cvt_pk_bf16_f32 v147, v157, s0
	v_addc_co_u32_e32 v157, vcc, 0, v167, vcc
	global_store_short v[156:157], v147, off offset:32
	v_add_co_u32_e32 v156, vcc, s66, v166
	v_cvt_pk_bf16_f32 v147, v154, s0
	s_nop 0
	v_addc_co_u32_e32 v157, vcc, 0, v167, vcc
	global_store_short v[156:157], v147, off offset:32
	v_add_co_u32_e32 v156, vcc, 0x410000, v166
	v_cvt_pk_bf16_f32 v147, v152, s0
	s_nop 0
	v_addc_co_u32_e32 v157, vcc, 0, v167, vcc
	v_add_co_u32_e32 v154, vcc, 0x18000, v166
	global_store_short v[156:157], v147, off offset:32
	v_cvt_pk_bf16_f32 v147, v155, s0
	v_addc_co_u32_e32 v155, vcc, 0, v167, vcc
	v_add_co_u32_e32 v152, vcc, 0x418000, v166
	global_store_short v[154:155], v147, off offset:32
	v_cvt_pk_bf16_f32 v147, v153, s0
	v_addc_co_u32_e32 v153, vcc, 0, v167, vcc
	global_store_short v[152:153], v147, off offset:32
.LBB0_598:
	v_add_u32_e32 v152, v143, v142
	v_mov_b32_e32 v153, v133
	v_lshl_add_u64 v[156:157], v[152:153], 3, s[40:41]
	s_nop 0
	s_and_b64 vcc, exec, s[0:1]
	s_waitcnt vmcnt(8)
	v_mov_b32_e32 v152, v220
	v_mov_b32_e32 v153, v221
	v_mov_b32_e32 v154, v222
	v_mov_b32_e32 v155, v223
	v_mov_b32_e32 v156, v224
	v_mov_b32_e32 v157, v225
	v_mov_b32_e32 v158, v226
	v_mov_b32_e32 v159, v227
	v_mov_b32_e32 v167, v154
	v_mov_b32_e32 v154, v153
	v_mov_b32_e32 v153, v158
	v_mov_b32_e32 v158, v157
	v_mov_b32_e32 v166, v152
	v_mov_b32_e32 v152, v156
	v_pk_mul_f32 v[156:157], v[104:105], v[154:155]
	v_pk_mul_f32 v[154:155], v[40:41], v[154:155]
	v_pk_mul_f32 v[168:169], v[106:107], v[158:159]
	v_pk_mul_f32 v[158:159], v[42:43], v[158:159]
	v_pk_fma_f32 v[156:157], v[40:41], v[166:167], v[156:157]
	v_pk_fma_f32 v[154:155], v[104:105], v[166:167], v[154:155] neg_lo:[0,0,1] neg_hi:[0,0,1]
	v_pk_fma_f32 v[166:167], v[42:43], v[152:153], v[168:169]
	v_pk_fma_f32 v[168:169], v[106:107], v[152:153], v[158:159] neg_lo:[0,0,1] neg_hi:[0,0,1]
	v_pk_mul_f32 v[158:159], v[134:135], v[154:155]
	v_pk_mul_f32 v[154:155], v[134:135], v[168:169]
	v_pk_mul_f32 v[156:157], v[134:135], v[156:157]
	v_pk_mul_f32 v[152:153], v[134:135], v[166:167]
	v_cvt_pk_bf16_f32 v166, v158, v159
	v_cvt_pk_bf16_f32 v167, v154, v155
	v_cvt_pk_bf16_f32 v168, v156, v157
	v_cvt_pk_bf16_f32 v169, v152, v153
	v_mov_b32_e32 v244, v166
	v_mov_b32_e32 v245, v167
	v_mov_b32_e32 v248, v168
	v_mov_b32_e32 v249, v169
	s_cbranch_vccnz .LBB0_600
	v_lshl_add_u64 v[166:167], v[128:129], 1, v[144:145]
	v_add_co_u32_e32 v168, vcc, 0x400000, v166
	v_cvt_pk_bf16_f32 v147, v158, s0
	s_nop 0
	v_addc_co_u32_e32 v169, vcc, 0, v167, vcc
	global_store_short v[166:167], v147, off offset:32
	v_cvt_pk_bf16_f32 v147, v156, s0
	v_add_co_u32_e32 v158, vcc, 0x8000, v166
	global_store_short v[168:169], v147, off offset:32
	v_cvt_pk_bf16_f32 v147, v159, s0
	v_addc_co_u32_e32 v159, vcc, 0, v167, vcc
	v_add_co_u32_e32 v156, vcc, 0x408000, v166
	global_store_short v[158:159], v147, off offset:32
	v_cvt_pk_bf16_f32 v147, v157, s0
	v_addc_co_u32_e32 v157, vcc, 0, v167, vcc
	global_store_short v[156:157], v147, off offset:32
	v_add_co_u32_e32 v156, vcc, s66, v166
	v_cvt_pk_bf16_f32 v147, v154, s0
	s_nop 0
	v_addc_co_u32_e32 v157, vcc, 0, v167, vcc
	global_store_short v[156:157], v147, off offset:32
	v_add_co_u32_e32 v156, vcc, 0x410000, v166
	v_cvt_pk_bf16_f32 v147, v152, s0
	s_nop 0
	v_addc_co_u32_e32 v157, vcc, 0, v167, vcc
	v_add_co_u32_e32 v154, vcc, 0x18000, v166
	global_store_short v[156:157], v147, off offset:32
	v_cvt_pk_bf16_f32 v147, v155, s0
	v_addc_co_u32_e32 v155, vcc, 0, v167, vcc
	v_add_co_u32_e32 v152, vcc, 0x418000, v166
	global_store_short v[154:155], v147, off offset:32
	v_cvt_pk_bf16_f32 v147, v153, s0
	v_addc_co_u32_e32 v153, vcc, 0, v167, vcc
	global_store_short v[152:153], v147, off offset:32
; __device__ __forceinline__ void gemm_tile(const TileDesc& td, char* shm_c, const int wv) {
;     ...
;   } else if (mode == EPI_ROPE_A) {
;     const float sc = td.scale;
;     #pragma unroll
;     for (int bj = 0; bj < 2; ++bj)
;     #pragma unroll
;     for (int n = 0; n < 2; ++n) {
;       int tok = td.bcol + bj * 128 + n * 16 + br_l;
;       int pos = tok & (SEQ - 1);
;       #pragma unroll
;       for (int m = 0; m < 4; ++m) {
;         int i0 = m * 16 + ar_l;
;         const float4* cs = (const float4*)(td.aux + ((long)pos * 128 + i0) * 2);
;         float4 c01 = cs[0], c23 = cs[1];
;         float cc[4] = {c01.x, c01.z, c23.x, c23.z}, ss[4] = {c01.y, c01.w, c23.y, c23.w};
;         f32x4 t1 = acc[0][bj][m][n], t2 = acc[1][bj][m][n], o1, o2;
;         #pragma unroll
;         for (int j = 0; j < 4; ++j) { o1[j] = (t1[j] * cc[j] - t2[j] * ss[j]) * sc; o2[j] = (t2[j] * cc[j] + t1[j] * ss[j]) * sc; }
;         long o = (long)tok * td.ldo + (td.brow + i0);
;         uint2 pk; pk.x = pack2(o1[0], o1[1]); pk.y = pack2(o1[2], o1[3]);
;         *(uint2*)(td.outb + o) = pk;
;         pk.x = pack2(o2[0], o2[1]); pk.y = pack2(o2[2], o2[3]);
;         *(uint2*)(td.outb + o + 128) = pk;
;         if (td.outT) {
;           u16* tp = td.outT + (long)i0 * LDT + tok;
;           #pragma unroll
;           for (int j = 0; j < 4; ++j) {
;             tp[(long)j * LDT] = (u16)(pack2(o1[j], 0.f) & 0xffffu);
;             tp[(long)(j + 128) * LDT] = (u16)(pack2(o2[j], 0.f) & 0xffffu);
;           }
;         }
;       }
;     }
.LBB0_600:
	v_add_u32_e32 v152, v143, v146
	v_mov_b32_e32 v153, v133
	v_lshl_add_u64 v[156:157], v[152:153], 3, s[40:41]
	s_nop 0
	s_and_b64 vcc, exec, s[0:1]
	s_waitcnt vmcnt(6)
	v_mov_b32_e32 v152, v228
	v_mov_b32_e32 v153, v229
	v_mov_b32_e32 v154, v230
	v_mov_b32_e32 v155, v231
	v_mov_b32_e32 v156, v232
	v_mov_b32_e32 v157, v233
	v_mov_b32_e32 v158, v234
	v_mov_b32_e32 v159, v235
	v_mov_b32_e32 v167, v154
	v_mov_b32_e32 v154, v153
	v_mov_b32_e32 v153, v158
	v_mov_b32_e32 v158, v157
	v_mov_b32_e32 v166, v152
	v_mov_b32_e32 v152, v156
	v_pk_mul_f32 v[156:157], v[96:97], v[154:155]
	v_pk_mul_f32 v[154:155], v[32:33], v[154:155]
	v_pk_mul_f32 v[168:169], v[98:99], v[158:159]
	v_pk_mul_f32 v[158:159], v[34:35], v[158:159]
	v_pk_fma_f32 v[156:157], v[32:33], v[166:167], v[156:157]
	v_pk_fma_f32 v[154:155], v[96:97], v[166:167], v[154:155] neg_lo:[0,0,1] neg_hi:[0,0,1]
	v_pk_fma_f32 v[166:167], v[34:35], v[152:153], v[168:169]
	v_pk_fma_f32 v[168:169], v[98:99], v[152:153], v[158:159] neg_lo:[0,0,1] neg_hi:[0,0,1]
	v_pk_mul_f32 v[158:159], v[134:135], v[154:155]
	v_pk_mul_f32 v[154:155], v[134:135], v[168:169]
	v_pk_mul_f32 v[156:157], v[134:135], v[156:157]
	v_pk_mul_f32 v[152:153], v[134:135], v[166:167]
	v_cvt_pk_bf16_f32 v166, v158, v159
	v_cvt_pk_bf16_f32 v167, v154, v155
	v_cvt_pk_bf16_f32 v168, v156, v157
	v_cvt_pk_bf16_f32 v169, v152, v153
	v_mov_b32_e32 v246, v166
	v_mov_b32_e32 v247, v167
	v_mov_b32_e32 v250, v168
	v_mov_b32_e32 v251, v169
	v_lshl_add_u64 v[170:171], v[150:151], 0, v[252:253]
	s_nop 0
	v_permlane16_swap_b32_e32 v244, v246
	v_permlane16_swap_b32_e32 v245, v247
	v_permlane16_swap_b32_e32 v248, v250
	v_permlane16_swap_b32_e32 v249, v251
	global_store_dwordx4 v[170:171], v[244:247], off offset:64
	global_store_dwordx4 v[170:171], v[248:251], off offset:320
	s_cbranch_vccnz .LBB0_602
	v_lshl_add_u64 v[150:151], v[128:129], 1, v[148:149]
	v_add_co_u32_e32 v166, vcc, 0x400000, v150
	v_cvt_pk_bf16_f32 v143, v158, s0
	s_nop 0
	v_addc_co_u32_e32 v167, vcc, 0, v151, vcc
	global_store_short v[150:151], v143, off offset:32
	v_cvt_pk_bf16_f32 v143, v156, s0
	v_add_co_u32_e32 v158, vcc, 0x8000, v150
	global_store_short v[166:167], v143, off offset:32
	v_cvt_pk_bf16_f32 v143, v159, s0
	v_addc_co_u32_e32 v159, vcc, 0, v151, vcc
	v_add_co_u32_e32 v156, vcc, 0x408000, v150
	global_store_short v[158:159], v143, off offset:32
	v_cvt_pk_bf16_f32 v143, v157, s0
	v_addc_co_u32_e32 v157, vcc, 0, v151, vcc
	global_store_short v[156:157], v143, off offset:32
	v_add_co_u32_e32 v156, vcc, s66, v150
	v_cvt_pk_bf16_f32 v143, v154, s0
	s_nop 0
	v_addc_co_u32_e32 v157, vcc, 0, v151, vcc
	global_store_short v[156:157], v143, off offset:32
	v_add_co_u32_e32 v156, vcc, 0x410000, v150
	v_cvt_pk_bf16_f32 v143, v152, s0
	s_nop 0
	v_addc_co_u32_e32 v157, vcc, 0, v151, vcc
	v_add_co_u32_e32 v154, vcc, 0x18000, v150
	global_store_short v[156:157], v143, off offset:32
	v_cvt_pk_bf16_f32 v143, v155, s0
	v_addc_co_u32_e32 v155, vcc, 0, v151, vcc
	v_add_co_u32_e32 v150, vcc, 0x418000, v150
	global_store_short v[154:155], v143, off offset:32
	v_cvt_pk_bf16_f32 v143, v153, s0
	v_addc_co_u32_e32 v151, vcc, 0, v151, vcc
	global_store_short v[150:151], v143, off offset:32
.LBB0_602:
	global_load_dwordx4 v[172:175], v[240:241], off
	global_load_dwordx4 v[176:179], v[240:241], off offset:16
	global_load_dwordx4 v[180:183], v[240:241], off offset:128
	global_load_dwordx4 v[184:187], v[240:241], off offset:144
	global_load_dwordx4 v[188:191], v[240:241], off offset:256
	global_load_dwordx4 v[192:195], v[240:241], off offset:272
	global_load_dwordx4 v[196:199], v[240:241], off offset:384
	global_load_dwordx4 v[200:203], v[240:241], off offset:400
	global_load_dwordx4 v[204:207], v[242:243], off
	global_load_dwordx4 v[208:211], v[242:243], off offset:16
	global_load_dwordx4 v[212:215], v[242:243], off offset:128
	global_load_dwordx4 v[216:219], v[242:243], off offset:144
	global_load_dwordx4 v[220:223], v[242:243], off offset:256
	global_load_dwordx4 v[224:227], v[242:243], off offset:272
	global_load_dwordx4 v[228:231], v[242:243], off offset:384
	global_load_dwordx4 v[232:235], v[242:243], off offset:400
	v_or_b32_e32 v147, 0x80, v128
	v_lshlrev_b32_e32 v143, 7, v147
	v_and_b32_e32 v143, 0x7f780, v143
	v_add_u32_e32 v150, v143, v136
	v_mov_b32_e32 v151, v133
	v_lshl_add_u64 v[150:151], v[150:151], 3, s[40:41]
	v_mul_lo_u32 v165, s35, v147
	v_mad_u64_u32 v[150:151], s[2:3], s34, v147, 0
	v_add3_u32 v151, v151, v137, v165
	v_lshl_add_u64 v[150:151], v[150:151], 1, s[36:37]
	s_and_b64 vcc, exec, s[0:1]
	v_lshl_add_u64 v[150:151], v[130:131], 1, v[150:151]
	s_waitcnt vmcnt(14)
	v_mov_b32_e32 v152, v172
	v_mov_b32_e32 v153, v173
	v_mov_b32_e32 v154, v174
	v_mov_b32_e32 v155, v175
	v_mov_b32_e32 v156, v176
	v_mov_b32_e32 v157, v177
	v_mov_b32_e32 v158, v178
	v_mov_b32_e32 v159, v179
	v_mov_b32_e32 v167, v154
	v_mov_b32_e32 v154, v153
	v_mov_b32_e32 v153, v158
	v_mov_b32_e32 v158, v157
	v_mov_b32_e32 v166, v152
	v_mov_b32_e32 v152, v156
	v_pk_mul_f32 v[156:157], v[92:93], v[154:155]
	v_pk_mul_f32 v[154:155], v[28:29], v[154:155]
	v_pk_mul_f32 v[168:169], v[94:95], v[158:159]
	v_pk_mul_f32 v[158:159], v[30:31], v[158:159]
	v_pk_fma_f32 v[156:157], v[28:29], v[166:167], v[156:157]
	v_pk_fma_f32 v[154:155], v[92:93], v[166:167], v[154:155] neg_lo:[0,0,1] neg_hi:[0,0,1]
	v_pk_fma_f32 v[166:167], v[30:31], v[152:153], v[168:169]
	v_pk_fma_f32 v[168:169], v[94:95], v[152:153], v[158:159] neg_lo:[0,0,1] neg_hi:[0,0,1]
	v_pk_mul_f32 v[158:159], v[134:135], v[154:155]
	v_pk_mul_f32 v[154:155], v[134:135], v[168:169]
	v_pk_mul_f32 v[156:157], v[134:135], v[156:157]
	v_pk_mul_f32 v[152:153], v[134:135], v[166:167]
	v_cvt_pk_bf16_f32 v166, v158, v159
	v_cvt_pk_bf16_f32 v167, v154, v155
	v_cvt_pk_bf16_f32 v168, v156, v157
	v_cvt_pk_bf16_f32 v169, v152, v153
	v_mov_b32_e32 v244, v166
	v_mov_b32_e32 v245, v167
	v_mov_b32_e32 v248, v168
	v_mov_b32_e32 v249, v169
	s_cbranch_vccnz .LBB0_604
; __device__ __forceinline__ void gemm_tile(const TileDesc& td, char* shm_c, const int wv) {
;     ...
;   } else if (mode == EPI_ROPE_A) {
;     const float sc = td.scale;
;     #pragma unroll
;     for (int bj = 0; bj < 2; ++bj)
;     #pragma unroll
;     for (int n = 0; n < 2; ++n) {
;       int tok = td.bcol + bj * 128 + n * 16 + br_l;
;       int pos = tok & (SEQ - 1);
;       #pragma unroll
;       for (int m = 0; m < 4; ++m) {
;         int i0 = m * 16 + ar_l;
;         const float4* cs = (const float4*)(td.aux + ((long)pos * 128 + i0) * 2);
;         float4 c01 = cs[0], c23 = cs[1];
;         float cc[4] = {c01.x, c01.z, c23.x, c23.z}, ss[4] = {c01.y, c01.w, c23.y, c23.w};
;         f32x4 t1 = acc[0][bj][m][n], t2 = acc[1][bj][m][n], o1, o2;
;         #pragma unroll
;         for (int j = 0; j < 4; ++j) { o1[j] = (t1[j] * cc[j] - t2[j] * ss[j]) * sc; o2[j] = (t2[j] * cc[j] + t1[j] * ss[j]) * sc; }
;         long o = (long)tok * td.ldo + (td.brow + i0);
;         uint2 pk; pk.x = pack2(o1[0], o1[1]); pk.y = pack2(o1[2], o1[3]);
;         *(uint2*)(td.outb + o) = pk;
;         pk.x = pack2(o2[0], o2[1]); pk.y = pack2(o2[2], o2[3]);
;         *(uint2*)(td.outb + o + 128) = pk;
;         if (td.outT) {
;           u16* tp = td.outT + (long)i0 * LDT + tok;
;           #pragma unroll
;           for (int j = 0; j < 4; ++j) {
;             tp[(long)j * LDT] = (u16)(pack2(o1[j], 0.f) & 0xffffu);
;             tp[(long)(j + 128) * LDT] = (u16)(pack2(o2[j], 0.f) & 0xffffu);
;           }
;         }
;       }
;     }
	v_lshl_add_u64 v[166:167], v[128:129], 1, v[138:139]
	v_add_co_u32_e32 v168, vcc, 0x400000, v166
	v_cvt_pk_bf16_f32 v147, v158, s0
	s_nop 0
	v_addc_co_u32_e32 v169, vcc, 0, v167, vcc
	global_store_short v[166:167], v147, off offset:256
	v_cvt_pk_bf16_f32 v147, v156, s0
	v_add_co_u32_e32 v158, vcc, 0x8000, v166
	global_store_short v[168:169], v147, off offset:256
	v_cvt_pk_bf16_f32 v147, v159, s0
	v_addc_co_u32_e32 v159, vcc, 0, v167, vcc
	v_add_co_u32_e32 v156, vcc, 0x408000, v166
	global_store_short v[158:159], v147, off offset:256
	v_cvt_pk_bf16_f32 v147, v157, s0
	v_addc_co_u32_e32 v157, vcc, 0, v167, vcc
	global_store_short v[156:157], v147, off offset:256
	v_add_co_u32_e32 v156, vcc, s66, v166
	v_cvt_pk_bf16_f32 v147, v154, s0
	s_nop 0
	v_addc_co_u32_e32 v157, vcc, 0, v167, vcc
	global_store_short v[156:157], v147, off offset:256
	v_add_co_u32_e32 v156, vcc, 0x410000, v166
	v_cvt_pk_bf16_f32 v147, v152, s0
	s_nop 0
	v_addc_co_u32_e32 v157, vcc, 0, v167, vcc
	v_add_co_u32_e32 v154, vcc, 0x18000, v166
	global_store_short v[156:157], v147, off offset:256
	v_cvt_pk_bf16_f32 v147, v155, s0
	v_addc_co_u32_e32 v155, vcc, 0, v167, vcc
	v_add_co_u32_e32 v152, vcc, 0x418000, v166
	global_store_short v[154:155], v147, off offset:256
	v_cvt_pk_bf16_f32 v147, v153, s0
	v_addc_co_u32_e32 v153, vcc, 0, v167, vcc
	global_store_short v[152:153], v147, off offset:256
.LBB0_604:
	v_add_u32_e32 v152, v143, v132
	v_mov_b32_e32 v153, v133
	v_lshl_add_u64 v[156:157], v[152:153], 3, s[40:41]
	s_nop 0
	s_and_b64 vcc, exec, s[0:1]
	s_waitcnt vmcnt(12)
	v_mov_b32_e32 v152, v180
	v_mov_b32_e32 v153, v181
	v_mov_b32_e32 v154, v182
	v_mov_b32_e32 v155, v183
	v_mov_b32_e32 v156, v184
	v_mov_b32_e32 v157, v185
	v_mov_b32_e32 v158, v186
	v_mov_b32_e32 v159, v187
	v_mov_b32_e32 v167, v154
	v_mov_b32_e32 v154, v153
	v_mov_b32_e32 v153, v158
	v_mov_b32_e32 v158, v157
	v_mov_b32_e32 v166, v152
	v_mov_b32_e32 v152, v156
	v_pk_mul_f32 v[156:157], v[84:85], v[154:155]
	v_pk_mul_f32 v[154:155], v[20:21], v[154:155]
	v_pk_mul_f32 v[168:169], v[86:87], v[158:159]
	v_pk_mul_f32 v[158:159], v[22:23], v[158:159]
	v_pk_fma_f32 v[156:157], v[20:21], v[166:167], v[156:157]
	v_pk_fma_f32 v[154:155], v[84:85], v[166:167], v[154:155] neg_lo:[0,0,1] neg_hi:[0,0,1]
	v_pk_fma_f32 v[166:167], v[22:23], v[152:153], v[168:169]
	v_pk_fma_f32 v[168:169], v[86:87], v[152:153], v[158:159] neg_lo:[0,0,1] neg_hi:[0,0,1]
	v_pk_mul_f32 v[158:159], v[134:135], v[154:155]
	v_pk_mul_f32 v[154:155], v[134:135], v[168:169]
	v_pk_mul_f32 v[156:157], v[134:135], v[156:157]
	v_pk_mul_f32 v[152:153], v[134:135], v[166:167]
	v_cvt_pk_bf16_f32 v166, v158, v159
	v_cvt_pk_bf16_f32 v167, v154, v155
	v_cvt_pk_bf16_f32 v168, v156, v157
	v_cvt_pk_bf16_f32 v169, v152, v153
	v_mov_b32_e32 v246, v166
	v_mov_b32_e32 v247, v167
	v_mov_b32_e32 v250, v168
	v_mov_b32_e32 v251, v169
	v_lshl_add_u64 v[170:171], v[150:151], 0, v[252:253]
	s_nop 0
	v_permlane16_swap_b32_e32 v244, v246
	v_permlane16_swap_b32_e32 v245, v247
	v_permlane16_swap_b32_e32 v248, v250
	v_permlane16_swap_b32_e32 v249, v251
	global_store_dwordx4 v[170:171], v[244:247], off
	global_store_dwordx4 v[170:171], v[248:251], off offset:256
	s_cbranch_vccnz .LBB0_606
	v_lshl_add_u64 v[166:167], v[128:129], 1, v[140:141]
	v_add_co_u32_e32 v168, vcc, 0x400000, v166
	v_cvt_pk_bf16_f32 v147, v158, s0
	s_nop 0
	v_addc_co_u32_e32 v169, vcc, 0, v167, vcc
	global_store_short v[166:167], v147, off offset:256
	v_cvt_pk_bf16_f32 v147, v156, s0
	v_add_co_u32_e32 v158, vcc, 0x8000, v166
	global_store_short v[168:169], v147, off offset:256
	v_cvt_pk_bf16_f32 v147, v159, s0
	v_addc_co_u32_e32 v159, vcc, 0, v167, vcc
	v_add_co_u32_e32 v156, vcc, 0x408000, v166
	global_store_short v[158:159], v147, off offset:256
	v_cvt_pk_bf16_f32 v147, v157, s0
	v_addc_co_u32_e32 v157, vcc, 0, v167, vcc
	global_store_short v[156:157], v147, off offset:256
	v_add_co_u32_e32 v156, vcc, s66, v166
	v_cvt_pk_bf16_f32 v147, v154, s0
	s_nop 0
	v_addc_co_u32_e32 v157, vcc, 0, v167, vcc
	global_store_short v[156:157], v147, off offset:256
	v_add_co_u32_e32 v156, vcc, 0x410000, v166
	v_cvt_pk_bf16_f32 v147, v152, s0
	s_nop 0
	v_addc_co_u32_e32 v157, vcc, 0, v167, vcc
	v_add_co_u32_e32 v154, vcc, 0x18000, v166
	global_store_short v[156:157], v147, off offset:256
	v_cvt_pk_bf16_f32 v147, v155, s0
	v_addc_co_u32_e32 v155, vcc, 0, v167, vcc
	v_add_co_u32_e32 v152, vcc, 0x418000, v166
	global_store_short v[154:155], v147, off offset:256
	v_cvt_pk_bf16_f32 v147, v153, s0
	v_addc_co_u32_e32 v153, vcc, 0, v167, vcc
	global_store_short v[152:153], v147, off offset:256
; __device__ __forceinline__ void gemm_tile(const TileDesc& td, char* shm_c, const int wv) {
;     ...
;   } else if (mode == EPI_ROPE_A) {
;     const float sc = td.scale;
;     #pragma unroll
;     for (int bj = 0; bj < 2; ++bj)
;     #pragma unroll
;     for (int n = 0; n < 2; ++n) {
;       int tok = td.bcol + bj * 128 + n * 16 + br_l;
;       int pos = tok & (SEQ - 1);
;       #pragma unroll
;       for (int m = 0; m < 4; ++m) {
;         int i0 = m * 16 + ar_l;
;         const float4* cs = (const float4*)(td.aux + ((long)pos * 128 + i0) * 2);
;         float4 c01 = cs[0], c23 = cs[1];
;         float cc[4] = {c01.x, c01.z, c23.x, c23.z}, ss[4] = {c01.y, c01.w, c23.y, c23.w};
;         f32x4 t1 = acc[0][bj][m][n], t2 = acc[1][bj][m][n], o1, o2;
;         #pragma unroll
;         for (int j = 0; j < 4; ++j) { o1[j] = (t1[j] * cc[j] - t2[j] * ss[j]) * sc; o2[j] = (t2[j] * cc[j] + t1[j] * ss[j]) * sc; }
;         long o = (long)tok * td.ldo + (td.brow + i0);
;         uint2 pk; pk.x = pack2(o1[0], o1[1]); pk.y = pack2(o1[2], o1[3]);
;         *(uint2*)(td.outb + o) = pk;
;         pk.x = pack2(o2[0], o2[1]); pk.y = pack2(o2[2], o2[3]);
;         *(uint2*)(td.outb + o + 128) = pk;
;         if (td.outT) {
;           u16* tp = td.outT + (long)i0 * LDT + tok;
;           #pragma unroll
;           for (int j = 0; j < 4; ++j) {
;             tp[(long)j * LDT] = (u16)(pack2(o1[j], 0.f) & 0xffffu);
;             tp[(long)(j + 128) * LDT] = (u16)(pack2(o2[j], 0.f) & 0xffffu);
;           }
;         }
;       }
;     }
.LBB0_606:
	v_add_u32_e32 v152, v143, v142
	v_mov_b32_e32 v153, v133
	v_lshl_add_u64 v[156:157], v[152:153], 3, s[40:41]
	s_nop 0
	s_and_b64 vcc, exec, s[0:1]
	s_waitcnt vmcnt(12)
	v_mov_b32_e32 v152, v188
	v_mov_b32_e32 v153, v189
	v_mov_b32_e32 v154, v190
	v_mov_b32_e32 v155, v191
	v_mov_b32_e32 v156, v192
	v_mov_b32_e32 v157, v193
	v_mov_b32_e32 v158, v194
	v_mov_b32_e32 v159, v195
	v_mov_b32_e32 v167, v154
	v_mov_b32_e32 v154, v153
	v_mov_b32_e32 v153, v158
	v_mov_b32_e32 v158, v157
	v_mov_b32_e32 v166, v152
	v_mov_b32_e32 v152, v156
	v_pk_mul_f32 v[156:157], v[76:77], v[154:155]
	v_pk_mul_f32 v[154:155], v[12:13], v[154:155]
	v_pk_mul_f32 v[168:169], v[78:79], v[158:159]
	v_pk_mul_f32 v[158:159], v[14:15], v[158:159]
	v_pk_fma_f32 v[156:157], v[12:13], v[166:167], v[156:157]
	v_pk_fma_f32 v[154:155], v[76:77], v[166:167], v[154:155] neg_lo:[0,0,1] neg_hi:[0,0,1]
	v_pk_fma_f32 v[166:167], v[14:15], v[152:153], v[168:169]
	v_pk_fma_f32 v[168:169], v[78:79], v[152:153], v[158:159] neg_lo:[0,0,1] neg_hi:[0,0,1]
	v_pk_mul_f32 v[158:159], v[134:135], v[154:155]
	v_pk_mul_f32 v[154:155], v[134:135], v[168:169]
	v_pk_mul_f32 v[156:157], v[134:135], v[156:157]
	v_pk_mul_f32 v[152:153], v[134:135], v[166:167]
	v_cvt_pk_bf16_f32 v166, v158, v159
	v_cvt_pk_bf16_f32 v167, v154, v155
	v_cvt_pk_bf16_f32 v168, v156, v157
	v_cvt_pk_bf16_f32 v169, v152, v153
	v_mov_b32_e32 v244, v166
	v_mov_b32_e32 v245, v167
	v_mov_b32_e32 v248, v168
	v_mov_b32_e32 v249, v169
	s_cbranch_vccnz .LBB0_608
	v_lshl_add_u64 v[166:167], v[128:129], 1, v[144:145]
	v_add_co_u32_e32 v168, vcc, 0x400000, v166
	v_cvt_pk_bf16_f32 v147, v158, s0
	s_nop 0
	v_addc_co_u32_e32 v169, vcc, 0, v167, vcc
	global_store_short v[166:167], v147, off offset:256
	v_cvt_pk_bf16_f32 v147, v156, s0
	v_add_co_u32_e32 v158, vcc, 0x8000, v166
	global_store_short v[168:169], v147, off offset:256
	v_cvt_pk_bf16_f32 v147, v159, s0
	v_addc_co_u32_e32 v159, vcc, 0, v167, vcc
	v_add_co_u32_e32 v156, vcc, 0x408000, v166
	global_store_short v[158:159], v147, off offset:256
	v_cvt_pk_bf16_f32 v147, v157, s0
	v_addc_co_u32_e32 v157, vcc, 0, v167, vcc
	global_store_short v[156:157], v147, off offset:256
	v_add_co_u32_e32 v156, vcc, s66, v166
	v_cvt_pk_bf16_f32 v147, v154, s0
	s_nop 0
	v_addc_co_u32_e32 v157, vcc, 0, v167, vcc
	global_store_short v[156:157], v147, off offset:256
	v_add_co_u32_e32 v156, vcc, 0x410000, v166
	v_cvt_pk_bf16_f32 v147, v152, s0
	s_nop 0
	v_addc_co_u32_e32 v157, vcc, 0, v167, vcc
	v_add_co_u32_e32 v154, vcc, 0x18000, v166
	global_store_short v[156:157], v147, off offset:256
	v_cvt_pk_bf16_f32 v147, v155, s0
	v_addc_co_u32_e32 v155, vcc, 0, v167, vcc
	v_add_co_u32_e32 v152, vcc, 0x418000, v166
	global_store_short v[154:155], v147, off offset:256
	v_cvt_pk_bf16_f32 v147, v153, s0
	v_addc_co_u32_e32 v153, vcc, 0, v167, vcc
	global_store_short v[152:153], v147, off offset:256
.LBB0_608:
	v_add_u32_e32 v152, v143, v146
	v_mov_b32_e32 v153, v133
	v_lshl_add_u64 v[156:157], v[152:153], 3, s[40:41]
	s_nop 0
	s_and_b64 vcc, exec, s[0:1]
	s_waitcnt vmcnt(10)
	v_mov_b32_e32 v152, v196
	v_mov_b32_e32 v153, v197
	v_mov_b32_e32 v154, v198
	v_mov_b32_e32 v155, v199
	v_mov_b32_e32 v156, v200
	v_mov_b32_e32 v157, v201
	v_mov_b32_e32 v158, v202
	v_mov_b32_e32 v159, v203
	v_mov_b32_e32 v167, v154
	v_mov_b32_e32 v154, v153
	v_mov_b32_e32 v153, v158
	v_mov_b32_e32 v158, v157
	v_mov_b32_e32 v166, v152
	v_mov_b32_e32 v152, v156
	v_pk_mul_f32 v[156:157], v[68:69], v[154:155]
	v_pk_mul_f32 v[154:155], v[4:5], v[154:155]
	v_pk_mul_f32 v[168:169], v[70:71], v[158:159]
	v_pk_mul_f32 v[158:159], v[6:7], v[158:159]
	v_pk_fma_f32 v[156:157], v[4:5], v[166:167], v[156:157]
	v_pk_fma_f32 v[154:155], v[68:69], v[166:167], v[154:155] neg_lo:[0,0,1] neg_hi:[0,0,1]
	v_pk_fma_f32 v[166:167], v[6:7], v[152:153], v[168:169]
	v_pk_fma_f32 v[168:169], v[70:71], v[152:153], v[158:159] neg_lo:[0,0,1] neg_hi:[0,0,1]
	v_pk_mul_f32 v[158:159], v[134:135], v[154:155]
	v_pk_mul_f32 v[154:155], v[134:135], v[168:169]
	v_pk_mul_f32 v[156:157], v[134:135], v[156:157]
	v_pk_mul_f32 v[152:153], v[134:135], v[166:167]
	v_cvt_pk_bf16_f32 v166, v158, v159
	v_cvt_pk_bf16_f32 v167, v154, v155
	v_cvt_pk_bf16_f32 v168, v156, v157
	v_cvt_pk_bf16_f32 v169, v152, v153
	v_mov_b32_e32 v246, v166
	v_mov_b32_e32 v247, v167
	v_mov_b32_e32 v250, v168
	v_mov_b32_e32 v251, v169
	v_lshl_add_u64 v[170:171], v[150:151], 0, v[252:253]
	s_nop 0
	v_permlane16_swap_b32_e32 v244, v246
	v_permlane16_swap_b32_e32 v245, v247
	v_permlane16_swap_b32_e32 v248, v250
	v_permlane16_swap_b32_e32 v249, v251
	global_store_dwordx4 v[170:171], v[244:247], off offset:64
	global_store_dwordx4 v[170:171], v[248:251], off offset:320
	s_cbranch_vccnz .LBB0_610
	v_lshl_add_u64 v[150:151], v[128:129], 1, v[148:149]
	v_add_co_u32_e32 v166, vcc, 0x400000, v150
	v_cvt_pk_bf16_f32 v143, v158, s0
	s_nop 0
	v_addc_co_u32_e32 v167, vcc, 0, v151, vcc
	global_store_short v[150:151], v143, off offset:256
	v_cvt_pk_bf16_f32 v143, v156, s0
	v_add_co_u32_e32 v158, vcc, 0x8000, v150
	global_store_short v[166:167], v143, off offset:256
	v_cvt_pk_bf16_f32 v143, v159, s0
	v_addc_co_u32_e32 v159, vcc, 0, v151, vcc
	v_add_co_u32_e32 v156, vcc, 0x408000, v150
	global_store_short v[158:159], v143, off offset:256
	v_cvt_pk_bf16_f32 v143, v157, s0
	v_addc_co_u32_e32 v157, vcc, 0, v151, vcc
	global_store_short v[156:157], v143, off offset:256
	v_add_co_u32_e32 v156, vcc, s66, v150
	v_cvt_pk_bf16_f32 v143, v154, s0
	s_nop 0
	v_addc_co_u32_e32 v157, vcc, 0, v151, vcc
	global_store_short v[156:157], v143, off offset:256
	v_add_co_u32_e32 v156, vcc, 0x410000, v150
	v_cvt_pk_bf16_f32 v143, v152, s0
	s_nop 0
	v_addc_co_u32_e32 v157, vcc, 0, v151, vcc
	v_add_co_u32_e32 v154, vcc, 0x18000, v150
	global_store_short v[156:157], v143, off offset:256
	v_cvt_pk_bf16_f32 v143, v155, s0
	v_addc_co_u32_e32 v155, vcc, 0, v151, vcc
	v_add_co_u32_e32 v150, vcc, 0x418000, v150
	global_store_short v[154:155], v143, off offset:256
	v_cvt_pk_bf16_f32 v143, v153, s0
	v_addc_co_u32_e32 v151, vcc, 0, v151, vcc
	global_store_short v[150:151], v143, off offset:256
; __device__ __forceinline__ void gemm_tile(const TileDesc& td, char* shm_c, const int wv) {
;     ...
;   } else if (mode == EPI_ROPE_A) {
;     const float sc = td.scale;
;     #pragma unroll
;     for (int bj = 0; bj < 2; ++bj)
;     #pragma unroll
;     for (int n = 0; n < 2; ++n) {
;       int tok = td.bcol + bj * 128 + n * 16 + br_l;
;       int pos = tok & (SEQ - 1);
;       #pragma unroll
;       for (int m = 0; m < 4; ++m) {
;         int i0 = m * 16 + ar_l;
;         const float4* cs = (const float4*)(td.aux + ((long)pos * 128 + i0) * 2);
;         float4 c01 = cs[0], c23 = cs[1];
;         float cc[4] = {c01.x, c01.z, c23.x, c23.z}, ss[4] = {c01.y, c01.w, c23.y, c23.w};
;         f32x4 t1 = acc[0][bj][m][n], t2 = acc[1][bj][m][n], o1, o2;
;         #pragma unroll
;         for (int j = 0; j < 4; ++j) { o1[j] = (t1[j] * cc[j] - t2[j] * ss[j]) * sc; o2[j] = (t2[j] * cc[j] + t1[j] * ss[j]) * sc; }
;         long o = (long)tok * td.ldo + (td.brow + i0);
;         uint2 pk; pk.x = pack2(o1[0], o1[1]); pk.y = pack2(o1[2], o1[3]);
;         *(uint2*)(td.outb + o) = pk;
;         pk.x = pack2(o2[0], o2[1]); pk.y = pack2(o2[2], o2[3]);
;         *(uint2*)(td.outb + o + 128) = pk;
;         if (td.outT) {
;           u16* tp = td.outT + (long)i0 * LDT + tok;
;           #pragma unroll
;           for (int j = 0; j < 4; ++j) {
;             tp[(long)j * LDT] = (u16)(pack2(o1[j], 0.f) & 0xffffu);
;             tp[(long)(j + 128) * LDT] = (u16)(pack2(o2[j], 0.f) & 0xffffu);
;           }
;         }
;       }
;     }
.LBB0_610:
	v_or_b32_e32 v143, 0x90, v128
	v_lshlrev_b32_e32 v147, 7, v143
	v_and_b32_e32 v147, 0x7ff80, v147
	v_add_u32_e32 v150, v147, v136
	v_mov_b32_e32 v151, v133
	v_lshl_add_u64 v[154:155], v[150:151], 3, s[40:41]
	s_nop 0
	v_mul_lo_u32 v165, s35, v143
	v_mad_u64_u32 v[158:159], s[2:3], s34, v143, 0
	v_add3_u32 v159, v159, v137, v165
	v_lshl_add_u64 v[158:159], v[158:159], 1, s[36:37]
	v_lshl_add_u64 v[130:131], v[130:131], 1, v[158:159]
	s_and_b64 vcc, exec, s[0:1]
	s_waitcnt vmcnt(10)
	v_mov_b32_e32 v150, v204
	v_mov_b32_e32 v151, v205
	v_mov_b32_e32 v152, v206
	v_mov_b32_e32 v153, v207
	v_mov_b32_e32 v154, v208
	v_mov_b32_e32 v155, v209
	v_mov_b32_e32 v156, v210
	v_mov_b32_e32 v157, v211
	v_mov_b32_e32 v159, v152
	v_mov_b32_e32 v152, v151
	v_mov_b32_e32 v151, v156
	v_mov_b32_e32 v156, v155
	v_mov_b32_e32 v158, v150
	v_mov_b32_e32 v150, v154
	v_pk_mul_f32 v[154:155], v[88:89], v[152:153]
	v_pk_mul_f32 v[152:153], v[24:25], v[152:153]
	v_pk_mul_f32 v[166:167], v[90:91], v[156:157]
	v_pk_mul_f32 v[156:157], v[26:27], v[156:157]
	v_pk_fma_f32 v[154:155], v[24:25], v[158:159], v[154:155]
	v_pk_fma_f32 v[152:153], v[88:89], v[158:159], v[152:153] neg_lo:[0,0,1] neg_hi:[0,0,1]
	v_pk_fma_f32 v[158:159], v[26:27], v[150:151], v[166:167]
	v_pk_fma_f32 v[166:167], v[90:91], v[150:151], v[156:157] neg_lo:[0,0,1] neg_hi:[0,0,1]
	v_pk_mul_f32 v[156:157], v[134:135], v[152:153]
	v_pk_mul_f32 v[152:153], v[134:135], v[166:167]
	v_pk_mul_f32 v[154:155], v[134:135], v[154:155]
	v_pk_mul_f32 v[150:151], v[134:135], v[158:159]
	v_cvt_pk_bf16_f32 v158, v156, v157
	v_cvt_pk_bf16_f32 v159, v152, v153
	v_cvt_pk_bf16_f32 v166, v154, v155
	v_cvt_pk_bf16_f32 v167, v150, v151
	v_mov_b32_e32 v244, v158
	v_mov_b32_e32 v245, v159
	v_mov_b32_e32 v248, v166
	v_mov_b32_e32 v249, v167
	s_cbranch_vccnz .LBB0_612
	v_lshl_add_u64 v[138:139], v[128:129], 1, v[138:139]
	v_add_co_u32_e32 v158, vcc, 0x400000, v138
	v_cvt_pk_bf16_f32 v137, v156, s0
	s_nop 0
	v_addc_co_u32_e32 v159, vcc, 0, v139, vcc
	global_store_short v[138:139], v137, off offset:288
	v_cvt_pk_bf16_f32 v137, v154, s0
	v_add_co_u32_e32 v156, vcc, 0x8000, v138
	global_store_short v[158:159], v137, off offset:288
	v_cvt_pk_bf16_f32 v137, v157, s0
	v_addc_co_u32_e32 v157, vcc, 0, v139, vcc
	v_add_co_u32_e32 v154, vcc, 0x408000, v138
	global_store_short v[156:157], v137, off offset:288
	v_cvt_pk_bf16_f32 v137, v155, s0
	v_addc_co_u32_e32 v155, vcc, 0, v139, vcc
	global_store_short v[154:155], v137, off offset:288
	v_add_co_u32_e32 v154, vcc, s66, v138
	v_cvt_pk_bf16_f32 v137, v152, s0
	s_nop 0
	v_addc_co_u32_e32 v155, vcc, 0, v139, vcc
	global_store_short v[154:155], v137, off offset:288
	v_add_co_u32_e32 v154, vcc, 0x410000, v138
	v_cvt_pk_bf16_f32 v137, v150, s0
	s_nop 0
	v_addc_co_u32_e32 v155, vcc, 0, v139, vcc
	v_add_co_u32_e32 v152, vcc, 0x18000, v138
	global_store_short v[154:155], v137, off offset:288
	v_cvt_pk_bf16_f32 v137, v153, s0
	v_addc_co_u32_e32 v153, vcc, 0, v139, vcc
	v_add_co_u32_e32 v138, vcc, 0x418000, v138
	global_store_short v[152:153], v137, off offset:288
	v_cvt_pk_bf16_f32 v137, v151, s0
	v_addc_co_u32_e32 v139, vcc, 0, v139, vcc
	global_store_short v[138:139], v137, off offset:288
.LBB0_612:
	v_add_u32_e32 v132, v147, v132
	v_lshl_add_u64 v[138:139], v[132:133], 3, s[40:41]
	s_and_b64 vcc, exec, s[0:1]
	s_waitcnt vmcnt(8)
	v_mov_b32_e32 v150, v212
	v_mov_b32_e32 v151, v213
	v_mov_b32_e32 v152, v214
	v_mov_b32_e32 v153, v215
	v_mov_b32_e32 v154, v216
	v_mov_b32_e32 v155, v217
	v_mov_b32_e32 v156, v218
	v_mov_b32_e32 v157, v219
	v_mov_b32_e32 v139, v152
	v_mov_b32_e32 v152, v151
	v_mov_b32_e32 v151, v156
	v_mov_b32_e32 v156, v155
	v_mov_b32_e32 v138, v150
	v_mov_b32_e32 v150, v154
	v_pk_mul_f32 v[154:155], v[80:81], v[152:153]
	v_pk_mul_f32 v[152:153], v[16:17], v[152:153]
	v_pk_mul_f32 v[158:159], v[82:83], v[156:157]
	v_pk_mul_f32 v[156:157], v[18:19], v[156:157]
	v_pk_fma_f32 v[154:155], v[16:17], v[138:139], v[154:155]
	v_pk_fma_f32 v[138:139], v[80:81], v[138:139], v[152:153] neg_lo:[0,0,1] neg_hi:[0,0,1]
	v_pk_fma_f32 v[158:159], v[18:19], v[150:151], v[158:159]
	v_pk_fma_f32 v[150:151], v[82:83], v[150:151], v[156:157] neg_lo:[0,0,1] neg_hi:[0,0,1]
	v_pk_mul_f32 v[152:153], v[134:135], v[154:155]
	v_pk_mul_f32 v[154:155], v[134:135], v[138:139]
	v_pk_mul_f32 v[150:151], v[134:135], v[150:151]
	v_pk_mul_f32 v[138:139], v[134:135], v[158:159]
	v_cvt_pk_bf16_f32 v156, v154, v155
	v_cvt_pk_bf16_f32 v157, v150, v151
	v_cvt_pk_bf16_f32 v158, v152, v153
	v_cvt_pk_bf16_f32 v159, v138, v139
	v_mov_b32_e32 v246, v156
	v_mov_b32_e32 v247, v157
	v_mov_b32_e32 v250, v158
	v_mov_b32_e32 v251, v159
	v_lshl_add_u64 v[170:171], v[130:131], 0, v[252:253]
	s_nop 0
	v_permlane16_swap_b32_e32 v244, v246
	v_permlane16_swap_b32_e32 v245, v247
	v_permlane16_swap_b32_e32 v248, v250
	v_permlane16_swap_b32_e32 v249, v251
	global_store_dwordx4 v[170:171], v[244:247], off
	global_store_dwordx4 v[170:171], v[248:251], off offset:256
	s_cbranch_vccnz .LBB0_614
	v_lshl_add_u64 v[140:141], v[128:129], 1, v[140:141]
	v_add_co_u32_e32 v156, vcc, 0x400000, v140
	v_cvt_pk_bf16_f32 v132, v154, s0
	s_nop 0
	v_addc_co_u32_e32 v157, vcc, 0, v141, vcc
	global_store_short v[140:141], v132, off offset:288
	v_cvt_pk_bf16_f32 v132, v152, s0
	v_add_co_u32_e32 v154, vcc, 0x8000, v140
	global_store_short v[156:157], v132, off offset:288
	v_cvt_pk_bf16_f32 v132, v155, s0
	v_addc_co_u32_e32 v155, vcc, 0, v141, vcc
	v_add_co_u32_e32 v152, vcc, 0x408000, v140
	global_store_short v[154:155], v132, off offset:288
	v_cvt_pk_bf16_f32 v132, v153, s0
	v_addc_co_u32_e32 v153, vcc, 0, v141, vcc
	global_store_short v[152:153], v132, off offset:288
	v_add_co_u32_e32 v152, vcc, s66, v140
	v_cvt_pk_bf16_f32 v132, v150, s0
	s_nop 0
	v_addc_co_u32_e32 v153, vcc, 0, v141, vcc
	global_store_short v[152:153], v132, off offset:288
	v_add_co_u32_e32 v152, vcc, 0x410000, v140
	v_cvt_pk_bf16_f32 v132, v138, s0
	s_nop 0
	v_addc_co_u32_e32 v153, vcc, 0, v141, vcc
	v_add_co_u32_e32 v150, vcc, 0x18000, v140
	global_store_short v[152:153], v132, off offset:288
	v_cvt_pk_bf16_f32 v132, v151, s0
	v_addc_co_u32_e32 v151, vcc, 0, v141, vcc
	v_add_co_u32_e32 v138, vcc, 0x418000, v140
	global_store_short v[150:151], v132, off offset:288
	v_cvt_pk_bf16_f32 v132, v139, s0
	v_addc_co_u32_e32 v139, vcc, 0, v141, vcc
	global_store_short v[138:139], v132, off offset:288
; __device__ __forceinline__ void gemm_tile(const TileDesc& td, char* shm_c, const int wv) {
;     ...
;   } else if (mode == EPI_ROPE_A) {
;     const float sc = td.scale;
;     #pragma unroll
;     for (int bj = 0; bj < 2; ++bj)
;     #pragma unroll
;     for (int n = 0; n < 2; ++n) {
;       int tok = td.bcol + bj * 128 + n * 16 + br_l;
;       int pos = tok & (SEQ - 1);
;       #pragma unroll
;       for (int m = 0; m < 4; ++m) {
;         int i0 = m * 16 + ar_l;
;         const float4* cs = (const float4*)(td.aux + ((long)pos * 128 + i0) * 2);
;         float4 c01 = cs[0], c23 = cs[1];
;         float cc[4] = {c01.x, c01.z, c23.x, c23.z}, ss[4] = {c01.y, c01.w, c23.y, c23.w};
;         f32x4 t1 = acc[0][bj][m][n], t2 = acc[1][bj][m][n], o1, o2;
;         #pragma unroll
;         for (int j = 0; j < 4; ++j) { o1[j] = (t1[j] * cc[j] - t2[j] * ss[j]) * sc; o2[j] = (t2[j] * cc[j] + t1[j] * ss[j]) * sc; }
;         long o = (long)tok * td.ldo + (td.brow + i0);
;         uint2 pk; pk.x = pack2(o1[0], o1[1]); pk.y = pack2(o1[2], o1[3]);
;         *(uint2*)(td.outb + o) = pk;
;         pk.x = pack2(o2[0], o2[1]); pk.y = pack2(o2[2], o2[3]);
;         *(uint2*)(td.outb + o + 128) = pk;
;         if (td.outT) {
;           u16* tp = td.outT + (long)i0 * LDT + tok;
;           #pragma unroll
;           for (int j = 0; j < 4; ++j) {
;             tp[(long)j * LDT] = (u16)(pack2(o1[j], 0.f) & 0xffffu);
;             tp[(long)(j + 128) * LDT] = (u16)(pack2(o2[j], 0.f) & 0xffffu);
;           }
;         }
;       }
;     }
.LBB0_614:
	v_add_u32_e32 v132, v147, v142
	v_lshl_add_u64 v[142:143], v[132:133], 3, s[40:41]
	s_and_b64 vcc, exec, s[0:1]
	s_waitcnt vmcnt(8)
	v_mov_b32_e32 v138, v220
	v_mov_b32_e32 v139, v221
	v_mov_b32_e32 v140, v222
	v_mov_b32_e32 v141, v223
	v_mov_b32_e32 v150, v224
	v_mov_b32_e32 v151, v225
	v_mov_b32_e32 v152, v226
	v_mov_b32_e32 v153, v227
	v_mov_b32_e32 v143, v140
	v_mov_b32_e32 v140, v139
	v_mov_b32_e32 v139, v152
	v_mov_b32_e32 v152, v151
	v_mov_b32_e32 v142, v138
	v_mov_b32_e32 v138, v150
	v_pk_mul_f32 v[150:151], v[72:73], v[140:141]
	v_pk_mul_f32 v[140:141], v[8:9], v[140:141]
	v_pk_mul_f32 v[154:155], v[74:75], v[152:153]
	v_pk_mul_f32 v[152:153], v[10:11], v[152:153]
	v_pk_fma_f32 v[150:151], v[8:9], v[142:143], v[150:151]
	v_pk_fma_f32 v[140:141], v[72:73], v[142:143], v[140:141] neg_lo:[0,0,1] neg_hi:[0,0,1]
	v_pk_fma_f32 v[152:153], v[74:75], v[138:139], v[152:153] neg_lo:[0,0,1] neg_hi:[0,0,1]
	v_pk_fma_f32 v[154:155], v[10:11], v[138:139], v[154:155]
	v_pk_mul_f32 v[142:143], v[134:135], v[150:151]
	v_pk_mul_f32 v[150:151], v[134:135], v[140:141]
	v_pk_mul_f32 v[140:141], v[134:135], v[152:153]
	v_pk_mul_f32 v[138:139], v[134:135], v[154:155]
	v_cvt_pk_bf16_f32 v152, v150, v151
	v_cvt_pk_bf16_f32 v153, v140, v141
	v_cvt_pk_bf16_f32 v154, v142, v143
	v_cvt_pk_bf16_f32 v155, v138, v139
	v_mov_b32_e32 v244, v152
	v_mov_b32_e32 v245, v153
	v_mov_b32_e32 v248, v154
	v_mov_b32_e32 v249, v155
	s_cbranch_vccnz .LBB0_616
	v_lshl_add_u64 v[144:145], v[128:129], 1, v[144:145]
	v_add_co_u32_e32 v152, vcc, 0x400000, v144
	v_cvt_pk_bf16_f32 v132, v150, s0
	s_nop 0
	v_addc_co_u32_e32 v153, vcc, 0, v145, vcc
	global_store_short v[144:145], v132, off offset:288
	v_cvt_pk_bf16_f32 v132, v142, s0
	v_add_co_u32_e32 v150, vcc, 0x8000, v144
	global_store_short v[152:153], v132, off offset:288
	v_cvt_pk_bf16_f32 v132, v151, s0
	v_addc_co_u32_e32 v151, vcc, 0, v145, vcc
	v_add_co_u32_e32 v142, vcc, 0x408000, v144
	global_store_short v[150:151], v132, off offset:288
	v_cvt_pk_bf16_f32 v132, v143, s0
	v_addc_co_u32_e32 v143, vcc, 0, v145, vcc
	global_store_short v[142:143], v132, off offset:288
	v_add_co_u32_e32 v142, vcc, s66, v144
	v_cvt_pk_bf16_f32 v132, v140, s0
	s_nop 0
	v_addc_co_u32_e32 v143, vcc, 0, v145, vcc
	global_store_short v[142:143], v132, off offset:288
	v_add_co_u32_e32 v142, vcc, 0x410000, v144
	v_cvt_pk_bf16_f32 v132, v138, s0
	s_nop 0
	v_addc_co_u32_e32 v143, vcc, 0, v145, vcc
	v_add_co_u32_e32 v140, vcc, 0x18000, v144
	global_store_short v[142:143], v132, off offset:288
	v_cvt_pk_bf16_f32 v132, v141, s0
	v_addc_co_u32_e32 v141, vcc, 0, v145, vcc
	v_add_co_u32_e32 v138, vcc, 0x418000, v144
	global_store_short v[140:141], v132, off offset:288
	v_cvt_pk_bf16_f32 v132, v139, s0
	v_addc_co_u32_e32 v139, vcc, 0, v145, vcc
	global_store_short v[138:139], v132, off offset:288
.LBB0_616:
	v_add_u32_e32 v132, v147, v146
	v_lshl_add_u64 v[142:143], v[132:133], 3, s[40:41]
	s_nop 0
	s_and_b64 vcc, exec, s[0:1]
	s_waitcnt vmcnt(6)
	v_mov_b32_e32 v138, v228
	v_mov_b32_e32 v139, v229
	v_mov_b32_e32 v140, v230
	v_mov_b32_e32 v141, v231
	v_mov_b32_e32 v142, v232
	v_mov_b32_e32 v143, v233
	v_mov_b32_e32 v144, v234
	v_mov_b32_e32 v145, v235
	v_mov_b32_e32 v147, v140
	v_mov_b32_e32 v140, v139
	v_mov_b32_e32 v139, v144
	v_mov_b32_e32 v144, v143
	v_mov_b32_e32 v146, v138
	v_mov_b32_e32 v138, v142
	v_pk_mul_f32 v[142:143], v[64:65], v[140:141]
	v_pk_mul_f32 v[140:141], v[0:1], v[140:141]
	v_pk_mul_f32 v[150:151], v[66:67], v[144:145]
	v_pk_mul_f32 v[144:145], v[2:3], v[144:145]
	v_pk_fma_f32 v[142:143], v[0:1], v[146:147], v[142:143]
	v_pk_fma_f32 v[146:147], v[64:65], v[146:147], v[140:141] neg_lo:[0,0,1] neg_hi:[0,0,1]
	v_pk_fma_f32 v[150:151], v[2:3], v[138:139], v[150:151]
	v_pk_fma_f32 v[144:145], v[66:67], v[138:139], v[144:145] neg_lo:[0,0,1] neg_hi:[0,0,1]
	v_pk_mul_f32 v[140:141], v[134:135], v[142:143]
	v_pk_mul_f32 v[142:143], v[134:135], v[146:147]
	v_pk_mul_f32 v[138:139], v[134:135], v[150:151]
	v_pk_mul_f32 v[134:135], v[134:135], v[144:145]
	v_cvt_pk_bf16_f32 v144, v142, v143
	v_cvt_pk_bf16_f32 v145, v134, v135
	v_cvt_pk_bf16_f32 v146, v140, v141
	v_cvt_pk_bf16_f32 v147, v138, v139
	v_mov_b32_e32 v246, v144
	v_mov_b32_e32 v247, v145
	v_mov_b32_e32 v250, v146
	v_mov_b32_e32 v251, v147
	v_lshl_add_u64 v[170:171], v[130:131], 0, v[252:253]
	s_nop 0
	v_permlane16_swap_b32_e32 v244, v246
	v_permlane16_swap_b32_e32 v245, v247
	v_permlane16_swap_b32_e32 v248, v250
	v_permlane16_swap_b32_e32 v249, v251
	global_store_dwordx4 v[170:171], v[244:247], off offset:64
	global_store_dwordx4 v[170:171], v[248:251], off offset:320
	s_cbranch_vccnz .LBB0_618
	v_lshl_add_u64 v[128:129], v[128:129], 1, v[148:149]
	v_cvt_pk_bf16_f32 v130, v142, s0
	global_store_short v[128:129], v130, off offset:288
	v_add_co_u32_e32 v130, vcc, 0x400000, v128
	v_cvt_pk_bf16_f32 v132, v140, s0
	s_nop 0
	v_addc_co_u32_e32 v131, vcc, 0, v129, vcc
	global_store_short v[130:131], v132, off offset:288
	v_add_co_u32_e32 v130, vcc, 0x8000, v128
	v_cvt_pk_bf16_f32 v132, v143, s0
	s_nop 0
	v_addc_co_u32_e32 v131, vcc, 0, v129, vcc
	global_store_short v[130:131], v132, off offset:288
	v_add_co_u32_e32 v130, vcc, 0x408000, v128
	v_cvt_pk_bf16_f32 v132, v141, s0
	s_nop 0
	v_addc_co_u32_e32 v131, vcc, 0, v129, vcc
	global_store_short v[130:131], v132, off offset:288
	v_add_co_u32_e32 v130, vcc, s66, v128
	v_cvt_pk_bf16_f32 v132, v134, s0
	s_nop 0
	v_addc_co_u32_e32 v131, vcc, 0, v129, vcc
	global_store_short v[130:131], v132, off offset:288
	v_add_co_u32_e32 v130, vcc, 0x410000, v128
	v_cvt_pk_bf16_f32 v132, v138, s0
	s_nop 0
	v_addc_co_u32_e32 v131, vcc, 0, v129, vcc
	global_store_short v[130:131], v132, off offset:288
	v_add_co_u32_e32 v130, vcc, 0x18000, v128
	v_cvt_pk_bf16_f32 v132, v135, s0
	s_nop 0
	v_addc_co_u32_e32 v131, vcc, 0, v129, vcc
	v_add_co_u32_e32 v128, vcc, 0x418000, v128
	global_store_short v[130:131], v132, off offset:288
	v_cvt_pk_bf16_f32 v130, v139, s0
	v_addc_co_u32_e32 v129, vcc, 0, v129, vcc
	global_store_short v[128:129], v130, off offset:288
